# attention block epilogue rewritten: O staged through per-wave LDS, 16-byte row-contiguous silu(z) loads and O stores issued together (was 64 serialized 4-byte load/vmcnt0/store round trips per wave an
# speedup vs baseline: 1.0314x; 1.0218x over previous
.LBB0_692:
	s_waitcnt vmcnt(8)
	v_lshl_add_u32 v64, v199, 4, 0
	v_add_u32_e32 v64, 0x10800, v64
	s_waitcnt vmcnt(9)
	ds_write_b128 v206, v[108:111] offset:32768
	s_waitcnt vmcnt(8)
	ds_write_b128 v206, v[112:115] offset:40960
	ds_write_b128 v64, v[104:107]
	s_and_saveexec_b64 s[6:7], s[4:5]
	ds_write_b32 v205, v116
	s_or_b64 exec, exec, s[6:7]
	s_waitcnt lgkmcnt(0)
	ds_read_b128 v[76:79], v204
	ds_read_b128 v[72:75], v204 offset:32
	s_ashr_i32 s31, s30, 31
	ds_read_b128 v[68:71], v204 offset:64
	ds_read_b128 v[64:67], v204 offset:96
	s_lshl_b64 s[6:7], s[30:31], 12
	s_add_u32 s4, s22, s6
	s_addc_u32 s5, s23, s7
	s_mov_b64 s[6:7], s[4:5]
	v_and_b32_e32 v87, 63, v199
	v_lshrrev_b32_e32 v88, 3, v87
	v_and_b32_e32 v89, 7, v87
	v_lshlrev_b32_e32 v84, 12, v88
	v_lshl_or_b32 v84, v89, 4, v84
	s_lshl_b32 s31, s30, 8
	s_add_i32 s31, s31, 0x12800
	v_lshlrev_b32_e32 v85, 10, v201
	v_lshl_add_u32 v85, v200, 2, v85
	v_add_u32_e32 v85, s31, v85
	v_lshlrev_b32_e32 v86, 8, v88
	v_lshl_or_b32 v86, v89, 5, v86
	v_add_u32_e32 v86, s31, v86
	global_load_dwordx4 v[80:83], v84, s[6:7]
	s_add_u32 s6, s6, 0x8000
	s_addc_u32 s7, s7, 0
	global_load_dwordx4 v[104:107], v84, s[6:7]
	s_add_u32 s6, s6, 0x8000
	s_addc_u32 s7, s7, 0
	global_load_dwordx4 v[108:111], v84, s[6:7]
	s_add_u32 s6, s6, 0x8000
	s_addc_u32 s7, s7, 0
	global_load_dwordx4 v[112:115], v84, s[6:7]
	s_add_u32 s6, s6, 0x8000
	s_addc_u32 s7, s7, 0
	s_waitcnt lgkmcnt(0)
	v_rcp_f32_e32 v76, v76
	v_rcp_f32_e32 v77, v77
	v_rcp_f32_e32 v78, v78
	v_rcp_f32_e32 v79, v79
	v_rcp_f32_e32 v72, v72
	v_rcp_f32_e32 v73, v73
	v_rcp_f32_e32 v74, v74
	v_rcp_f32_e32 v75, v75
	v_rcp_f32_e32 v68, v68
	v_rcp_f32_e32 v69, v69
	v_rcp_f32_e32 v70, v70
	v_rcp_f32_e32 v71, v71
	v_rcp_f32_e32 v64, v64
	v_rcp_f32_e32 v65, v65
	v_rcp_f32_e32 v66, v66
	v_rcp_f32_e32 v67, v67
	v_mul_f32_e32 v32, v32, v76
	ds_write_b32 v85, v32
	v_mul_f32_e32 v48, v48, v76
	ds_write_b32 v85, v48 offset:128
	v_mul_f32_e32 v33, v33, v77
	ds_write_b32 v85, v33 offset:256
	v_mul_f32_e32 v49, v49, v77
	ds_write_b32 v85, v49 offset:384
	v_mul_f32_e32 v34, v34, v78
	ds_write_b32 v85, v34 offset:512
	v_mul_f32_e32 v50, v50, v78
	ds_write_b32 v85, v50 offset:640
	v_mul_f32_e32 v35, v35, v79
	ds_write_b32 v85, v35 offset:768
	v_mul_f32_e32 v51, v51, v79
	ds_write_b32 v85, v51 offset:896
	v_mul_f32_e32 v36, v36, v72
	ds_write_b32 v85, v36 offset:2048
	v_mul_f32_e32 v52, v52, v72
	ds_write_b32 v85, v52 offset:2176
	v_mul_f32_e32 v37, v37, v73
	ds_write_b32 v85, v37 offset:2304
	v_mul_f32_e32 v53, v53, v73
	ds_write_b32 v85, v53 offset:2432
	v_mul_f32_e32 v38, v38, v74
	ds_write_b32 v85, v38 offset:2560
	v_mul_f32_e32 v54, v54, v74
	ds_write_b32 v85, v54 offset:2688
	v_mul_f32_e32 v39, v39, v75
	ds_write_b32 v85, v39 offset:2816
	v_mul_f32_e32 v55, v55, v75
	ds_write_b32 v85, v55 offset:2944
	v_mul_f32_e32 v40, v40, v68
	ds_write_b32 v85, v40 offset:4096
	v_mul_f32_e32 v56, v56, v68
	ds_write_b32 v85, v56 offset:4224
	v_mul_f32_e32 v41, v41, v69
	ds_write_b32 v85, v41 offset:4352
	v_mul_f32_e32 v57, v57, v69
	ds_write_b32 v85, v57 offset:4480
	v_mul_f32_e32 v42, v42, v70
	ds_write_b32 v85, v42 offset:4608
	v_mul_f32_e32 v58, v58, v70
	ds_write_b32 v85, v58 offset:4736
	v_mul_f32_e32 v43, v43, v71
	ds_write_b32 v85, v43 offset:4864
	v_mul_f32_e32 v59, v59, v71
	ds_write_b32 v85, v59 offset:4992
	v_mul_f32_e32 v44, v44, v64
	ds_write_b32 v85, v44 offset:6144
	v_mul_f32_e32 v60, v60, v64
	ds_write_b32 v85, v60 offset:6272
	v_mul_f32_e32 v45, v45, v65
	ds_write_b32 v85, v45 offset:6400
	v_mul_f32_e32 v61, v61, v65
	ds_write_b32 v85, v61 offset:6528
	v_mul_f32_e32 v46, v46, v66
	ds_write_b32 v85, v46 offset:6656
	v_mul_f32_e32 v62, v62, v66
	ds_write_b32 v85, v62 offset:6784
	v_mul_f32_e32 v47, v47, v67
	ds_write_b32 v85, v47 offset:6912
	v_mul_f32_e32 v63, v63, v67
	ds_write_b32 v85, v63 offset:7040
	s_sub_u32 s6, s6, 0x20000
	s_subb_u32 s7, s7, 0
	global_load_dwordx4 v[32:35], v84, s[6:7] offset:128
	s_add_u32 s6, s6, 0x8000
	s_addc_u32 s7, s7, 0
	global_load_dwordx4 v[36:39], v84, s[6:7] offset:128
	s_add_u32 s6, s6, 0x8000
	s_addc_u32 s7, s7, 0
	global_load_dwordx4 v[40:43], v84, s[6:7] offset:128
	s_add_u32 s6, s6, 0x8000
	s_addc_u32 s7, s7, 0
	global_load_dwordx4 v[44:47], v84, s[6:7] offset:128
	s_add_u32 s6, s6, 0x8000
	s_addc_u32 s7, s7, 0
	ds_read_b128 v[48:51], v86
	ds_read_b128 v[52:55], v86 offset:16
	s_waitcnt vmcnt(7)
	v_lshlrev_b32_e32 v56, 16, v80
	v_and_b32_e32 v57, 0xffff0000, v80
	v_lshlrev_b32_e32 v58, 16, v81
	v_and_b32_e32 v59, 0xffff0000, v81
	v_lshlrev_b32_e32 v60, 16, v82
	v_and_b32_e32 v61, 0xffff0000, v82
	v_lshlrev_b32_e32 v62, 16, v83
	v_and_b32_e32 v63, 0xffff0000, v83
	s_waitcnt lgkmcnt(0)
	v_mul_f32_e32 v48, v48, v56
	v_mul_f32_e32 v49, v49, v57
	v_mul_f32_e32 v50, v50, v58
	v_mul_f32_e32 v51, v51, v59
	v_mul_f32_e32 v52, v52, v60
	v_mul_f32_e32 v53, v53, v61
	v_mul_f32_e32 v54, v54, v62
	v_mul_f32_e32 v55, v55, v63
	v_cvt_pk_bf16_f32 v56, v48, v49
	v_cvt_pk_bf16_f32 v57, v50, v51
	v_cvt_pk_bf16_f32 v58, v52, v53
	v_cvt_pk_bf16_f32 v59, v54, v55
	global_store_dwordx4 v84, v[56:59], s[4:5]
	s_add_u32 s4, s4, 0x8000
	s_addc_u32 s5, s5, 0
	ds_read_b128 v[48:51], v86 offset:2048
	ds_read_b128 v[52:55], v86 offset:2064
	s_waitcnt vmcnt(7)
	v_lshlrev_b32_e32 v56, 16, v104
	v_and_b32_e32 v57, 0xffff0000, v104
	v_lshlrev_b32_e32 v58, 16, v105
	v_and_b32_e32 v59, 0xffff0000, v105
	v_lshlrev_b32_e32 v60, 16, v106
	v_and_b32_e32 v61, 0xffff0000, v106
	v_lshlrev_b32_e32 v62, 16, v107
	v_and_b32_e32 v63, 0xffff0000, v107
	s_waitcnt lgkmcnt(0)
	v_mul_f32_e32 v48, v48, v56
	v_mul_f32_e32 v49, v49, v57
	v_mul_f32_e32 v50, v50, v58
	v_mul_f32_e32 v51, v51, v59
	v_mul_f32_e32 v52, v52, v60
	v_mul_f32_e32 v53, v53, v61
	v_mul_f32_e32 v54, v54, v62
	v_mul_f32_e32 v55, v55, v63
	v_cvt_pk_bf16_f32 v56, v48, v49
	v_cvt_pk_bf16_f32 v57, v50, v51
	v_cvt_pk_bf16_f32 v58, v52, v53
	v_cvt_pk_bf16_f32 v59, v54, v55
	global_store_dwordx4 v84, v[56:59], s[4:5]
	s_add_u32 s4, s4, 0x8000
	s_addc_u32 s5, s5, 0
	ds_read_b128 v[48:51], v86 offset:4096
	ds_read_b128 v[52:55], v86 offset:4112
	s_waitcnt vmcnt(7)
	v_lshlrev_b32_e32 v56, 16, v108
	v_and_b32_e32 v57, 0xffff0000, v108
	v_lshlrev_b32_e32 v58, 16, v109
	v_and_b32_e32 v59, 0xffff0000, v109
	v_lshlrev_b32_e32 v60, 16, v110
	v_and_b32_e32 v61, 0xffff0000, v110
	v_lshlrev_b32_e32 v62, 16, v111
	v_and_b32_e32 v63, 0xffff0000, v111
	s_waitcnt lgkmcnt(0)
	v_mul_f32_e32 v48, v48, v56
	v_mul_f32_e32 v49, v49, v57
	v_mul_f32_e32 v50, v50, v58
	v_mul_f32_e32 v51, v51, v59
	v_mul_f32_e32 v52, v52, v60
	v_mul_f32_e32 v53, v53, v61
	v_mul_f32_e32 v54, v54, v62
	v_mul_f32_e32 v55, v55, v63
	v_cvt_pk_bf16_f32 v56, v48, v49
	v_cvt_pk_bf16_f32 v57, v50, v51
	v_cvt_pk_bf16_f32 v58, v52, v53
	v_cvt_pk_bf16_f32 v59, v54, v55
	global_store_dwordx4 v84, v[56:59], s[4:5]
	s_add_u32 s4, s4, 0x8000
	s_addc_u32 s5, s5, 0
	ds_read_b128 v[48:51], v86 offset:6144
	ds_read_b128 v[52:55], v86 offset:6160
	s_waitcnt vmcnt(7)
	v_lshlrev_b32_e32 v56, 16, v112
	v_and_b32_e32 v57, 0xffff0000, v112
	v_lshlrev_b32_e32 v58, 16, v113
	v_and_b32_e32 v59, 0xffff0000, v113
	v_lshlrev_b32_e32 v60, 16, v114
	v_and_b32_e32 v61, 0xffff0000, v114
	v_lshlrev_b32_e32 v62, 16, v115
	v_and_b32_e32 v63, 0xffff0000, v115
	s_waitcnt lgkmcnt(0)
	v_mul_f32_e32 v48, v48, v56
	v_mul_f32_e32 v49, v49, v57
	v_mul_f32_e32 v50, v50, v58
	v_mul_f32_e32 v51, v51, v59
	v_mul_f32_e32 v52, v52, v60
	v_mul_f32_e32 v53, v53, v61
	v_mul_f32_e32 v54, v54, v62
	v_mul_f32_e32 v55, v55, v63
	v_cvt_pk_bf16_f32 v56, v48, v49
	v_cvt_pk_bf16_f32 v57, v50, v51
	v_cvt_pk_bf16_f32 v58, v52, v53
	v_cvt_pk_bf16_f32 v59, v54, v55
	global_store_dwordx4 v84, v[56:59], s[4:5]
	s_add_u32 s4, s4, 0x8000
	s_addc_u32 s5, s5, 0
	v_mul_f32_e32 v16, v16, v76
	ds_write_b32 v85, v16
	v_mul_f32_e32 v0, v0, v76
	ds_write_b32 v85, v0 offset:128
	v_mul_f32_e32 v17, v17, v77
	ds_write_b32 v85, v17 offset:256
	v_mul_f32_e32 v1, v1, v77
	ds_write_b32 v85, v1 offset:384
	v_mul_f32_e32 v18, v18, v78
	ds_write_b32 v85, v18 offset:512
	v_mul_f32_e32 v2, v2, v78
	ds_write_b32 v85, v2 offset:640
	v_mul_f32_e32 v19, v19, v79
	ds_write_b32 v85, v19 offset:768
	v_mul_f32_e32 v3, v3, v79
	ds_write_b32 v85, v3 offset:896
	v_mul_f32_e32 v20, v20, v72
	ds_write_b32 v85, v20 offset:2048
	v_mul_f32_e32 v4, v4, v72
	ds_write_b32 v85, v4 offset:2176
	v_mul_f32_e32 v21, v21, v73
	ds_write_b32 v85, v21 offset:2304
	v_mul_f32_e32 v5, v5, v73
	ds_write_b32 v85, v5 offset:2432
	v_mul_f32_e32 v22, v22, v74
	ds_write_b32 v85, v22 offset:2560
	v_mul_f32_e32 v6, v6, v74
	ds_write_b32 v85, v6 offset:2688
	v_mul_f32_e32 v23, v23, v75
	ds_write_b32 v85, v23 offset:2816
	v_mul_f32_e32 v7, v7, v75
	ds_write_b32 v85, v7 offset:2944
	v_mul_f32_e32 v24, v24, v68
	ds_write_b32 v85, v24 offset:4096
	v_mul_f32_e32 v8, v8, v68
	ds_write_b32 v85, v8 offset:4224
	v_mul_f32_e32 v25, v25, v69
	ds_write_b32 v85, v25 offset:4352
	v_mul_f32_e32 v9, v9, v69
	ds_write_b32 v85, v9 offset:4480
	v_mul_f32_e32 v26, v26, v70
	ds_write_b32 v85, v26 offset:4608
	v_mul_f32_e32 v10, v10, v70
	ds_write_b32 v85, v10 offset:4736
	v_mul_f32_e32 v27, v27, v71
	ds_write_b32 v85, v27 offset:4864
	v_mul_f32_e32 v11, v11, v71
	ds_write_b32 v85, v11 offset:4992
	v_mul_f32_e32 v28, v28, v64
	ds_write_b32 v85, v28 offset:6144
	v_mul_f32_e32 v12, v12, v64
	ds_write_b32 v85, v12 offset:6272
	v_mul_f32_e32 v29, v29, v65
	ds_write_b32 v85, v29 offset:6400
	v_mul_f32_e32 v13, v13, v65
	ds_write_b32 v85, v13 offset:6528
	v_mul_f32_e32 v30, v30, v66
	ds_write_b32 v85, v30 offset:6656
	v_mul_f32_e32 v14, v14, v66
	ds_write_b32 v85, v14 offset:6784
	v_mul_f32_e32 v31, v31, v67
	ds_write_b32 v85, v31 offset:6912
	v_mul_f32_e32 v15, v15, v67
	ds_write_b32 v85, v15 offset:7040
	s_sub_u32 s4, s4, 0x20000
	s_subb_u32 s5, s5, 0
	ds_read_b128 v[48:51], v86
	ds_read_b128 v[52:55], v86 offset:16
	s_waitcnt vmcnt(7)
	v_lshlrev_b32_e32 v56, 16, v32
	v_and_b32_e32 v57, 0xffff0000, v32
	v_lshlrev_b32_e32 v58, 16, v33
	v_and_b32_e32 v59, 0xffff0000, v33
	v_lshlrev_b32_e32 v60, 16, v34
	v_and_b32_e32 v61, 0xffff0000, v34
	v_lshlrev_b32_e32 v62, 16, v35
	v_and_b32_e32 v63, 0xffff0000, v35
	s_waitcnt lgkmcnt(0)
	v_mul_f32_e32 v48, v48, v56
	v_mul_f32_e32 v49, v49, v57
	v_mul_f32_e32 v50, v50, v58
	v_mul_f32_e32 v51, v51, v59
	v_mul_f32_e32 v52, v52, v60
	v_mul_f32_e32 v53, v53, v61
	v_mul_f32_e32 v54, v54, v62
	v_mul_f32_e32 v55, v55, v63
	v_cvt_pk_bf16_f32 v56, v48, v49
	v_cvt_pk_bf16_f32 v57, v50, v51
	v_cvt_pk_bf16_f32 v58, v52, v53
	v_cvt_pk_bf16_f32 v59, v54, v55
	global_store_dwordx4 v84, v[56:59], s[4:5] offset:128
	s_add_u32 s4, s4, 0x8000
	s_addc_u32 s5, s5, 0
	ds_read_b128 v[48:51], v86 offset:2048
	ds_read_b128 v[52:55], v86 offset:2064
	s_waitcnt vmcnt(7)
	v_lshlrev_b32_e32 v56, 16, v36
	v_and_b32_e32 v57, 0xffff0000, v36
	v_lshlrev_b32_e32 v58, 16, v37
	v_and_b32_e32 v59, 0xffff0000, v37
	v_lshlrev_b32_e32 v60, 16, v38
	v_and_b32_e32 v61, 0xffff0000, v38
	v_lshlrev_b32_e32 v62, 16, v39
	v_and_b32_e32 v63, 0xffff0000, v39
	s_waitcnt lgkmcnt(0)
	v_mul_f32_e32 v48, v48, v56
	v_mul_f32_e32 v49, v49, v57
	v_mul_f32_e32 v50, v50, v58
	v_mul_f32_e32 v51, v51, v59
	v_mul_f32_e32 v52, v52, v60
	v_mul_f32_e32 v53, v53, v61
	v_mul_f32_e32 v54, v54, v62
	v_mul_f32_e32 v55, v55, v63
	v_cvt_pk_bf16_f32 v56, v48, v49
	v_cvt_pk_bf16_f32 v57, v50, v51
	v_cvt_pk_bf16_f32 v58, v52, v53
	v_cvt_pk_bf16_f32 v59, v54, v55
	global_store_dwordx4 v84, v[56:59], s[4:5] offset:128
	s_add_u32 s4, s4, 0x8000
	s_addc_u32 s5, s5, 0
	ds_read_b128 v[48:51], v86 offset:4096
	ds_read_b128 v[52:55], v86 offset:4112
	s_waitcnt vmcnt(7)
	v_lshlrev_b32_e32 v56, 16, v40
	v_and_b32_e32 v57, 0xffff0000, v40
	v_lshlrev_b32_e32 v58, 16, v41
	v_and_b32_e32 v59, 0xffff0000, v41
	v_lshlrev_b32_e32 v60, 16, v42
	v_and_b32_e32 v61, 0xffff0000, v42
	v_lshlrev_b32_e32 v62, 16, v43
	v_and_b32_e32 v63, 0xffff0000, v43
	s_waitcnt lgkmcnt(0)
	v_mul_f32_e32 v48, v48, v56
	v_mul_f32_e32 v49, v49, v57
	v_mul_f32_e32 v50, v50, v58
	v_mul_f32_e32 v51, v51, v59
	v_mul_f32_e32 v52, v52, v60
	v_mul_f32_e32 v53, v53, v61
	v_mul_f32_e32 v54, v54, v62
	v_mul_f32_e32 v55, v55, v63
	v_cvt_pk_bf16_f32 v56, v48, v49
	v_cvt_pk_bf16_f32 v57, v50, v51
	v_cvt_pk_bf16_f32 v58, v52, v53
	v_cvt_pk_bf16_f32 v59, v54, v55
	global_store_dwordx4 v84, v[56:59], s[4:5] offset:128
	s_add_u32 s4, s4, 0x8000
	s_addc_u32 s5, s5, 0
	ds_read_b128 v[48:51], v86 offset:6144
	ds_read_b128 v[52:55], v86 offset:6160
	s_waitcnt vmcnt(7)
	v_lshlrev_b32_e32 v56, 16, v44
	v_and_b32_e32 v57, 0xffff0000, v44
	v_lshlrev_b32_e32 v58, 16, v45
	v_and_b32_e32 v59, 0xffff0000, v45
	v_lshlrev_b32_e32 v60, 16, v46
	v_and_b32_e32 v61, 0xffff0000, v46
	v_lshlrev_b32_e32 v62, 16, v47
	v_and_b32_e32 v63, 0xffff0000, v47
	s_waitcnt lgkmcnt(0)
	v_mul_f32_e32 v48, v48, v56
	v_mul_f32_e32 v49, v49, v57
	v_mul_f32_e32 v50, v50, v58
	v_mul_f32_e32 v51, v51, v59
	v_mul_f32_e32 v52, v52, v60
	v_mul_f32_e32 v53, v53, v61
	v_mul_f32_e32 v54, v54, v62
	v_mul_f32_e32 v55, v55, v63
	v_cvt_pk_bf16_f32 v56, v48, v49
	v_cvt_pk_bf16_f32 v57, v50, v51
	v_cvt_pk_bf16_f32 v58, v52, v53
	v_cvt_pk_bf16_f32 v59, v54, v55
	global_store_dwordx4 v84, v[56:59], s[4:5] offset:128
	s_add_u32 s4, s4, 0x8000
	s_addc_u32 s5, s5, 0
	s_waitcnt vmcnt(8)
	s_branch .LBB0_658
